# OUTNORM_C split: half-0 rows normalised by the workgroups idle during SCAN_C (after their deferred convert); the OUTNORM_C phase, hand-written with DPP reductions, handles only half-1 rows
# baseline (speedup 1.0000x reference)
; DI float shx(float v, int m) { return __int_as_float(__builtin_amdgcn_ds_bpermute((lane_now() ^ m) << 2, __float_as_int(v))); }
; DI int shx(int v, int m) { return __builtin_amdgcn_ds_bpermute((lane_now() ^ m) << 2, v); }
; DI u16 f2bf(float x) { return (u16)(pk2bf(x, 0.f) & 0xffffu); }
; DI float bfs(short v) { return __uint_as_float(((unsigned)(u16)v) << 16); }
; DI void phase_outnorm_c(int wv_, int vb_, int nvb_, char* ws_, const Ctx& p) {
;   u16* O = (u16*)(ws_ + WS_H); const u16* G = (const u16*)(ws_ + WS_CG);
;   const int tid = tidx(wv_); const int e = tid & 15;
;   float og[8];
; #pragma unroll
;   for (int j = 0; j < 8; ++j) og[j] = p.c_o_gain[e * 8 + j];
;   const size_t stride = (size_t)nvb_ * 256, total = (size_t)NTOK * 8 * 16;
;   for (size_t idx0 = (size_t)vb_ * 256 + tid; idx0 < total; idx0 += 4 * stride) {
;     bf16x8 ov[4], gv[4]; bool ok[4];
; #pragma unroll
;     for (int q = 0; q < 4; ++q) { const size_t idx = idx0 + q * stride; ok[q] = idx < total; const size_t rowh = (ok[q] ? idx : idx0) >> 4;
;       ov[q] = *(const bf16x8*)(O + rowh * 128 + e * 8); gv[q] = *(const bf16x8*)(G + rowh * 128 + e * 8); }
; #pragma unroll
;     for (int q = 0; q < 4; ++q) {
;       float f[8]; float ss = 0.f;
; #pragma unroll
;       for (int j = 0; j < 8; ++j) { f[j] = bfs(ov[q][j]); ss += f[j] * f[j]; }
;       ss += shx(ss, 1); ss += shx(ss, 2); ss += shx(ss, 4); ss += shx(ss, 8);
;       const float rn = rsqrtf(ss * (1.0f / 128.0f) + 1e-6f);
;       bf16x8 o;
; #pragma unroll
;       for (int j = 0; j < 8; ++j) { float gt = bfs(gv[q][j]); float sl = gt * __builtin_amdgcn_rcpf(1.0f + __expf(-gt)); o[j] = (short)f2bf(f[j] * rn * og[j] * sl); }
;       if (ok[q]) *(bf16x8*)(O + ((idx0 + q * stride) >> 4) * 128 + e * 8) = o;
;     }
.LBB0_211:
	s_andn2_b64 vcc, exec, s[2:3]
	s_cbranch_vccnz .LBB0_235
	s_cmp_gt_i32 s23, 8
	s_mov_b64 s[2:3], -1
	s_cbranch_scc0 .LBB0_223
	v_lshl_or_b32 v10, s33, 6, v204
	v_and_b32_e32 v11, 15, v10
	v_lshrrev_b32_e32 v12, 4, v10
	v_lshlrev_b32_e32 v13, 11, v12
	v_lshl_add_u32 v13, v11, 4, v13
	v_readlane_b32 s8, v254, 28
	v_readlane_b32 s9, v254, 29
	v_lshlrev_b32_e32 v14, 5, v11
	v_readlane_b32 s10, v254, 14
	s_nop 4
	global_load_dwordx4 v[2:5], v14, s[8:9]
	global_load_dwordx4 v[6:9], v14, s[8:9] offset:16
.Lonp_loop:
	s_nop 0
	s_nop 0
	s_nop 0
	s_nop 0
	s_nop 0
	s_nop 0
	s_nop 0
	s_nop 0
	s_nop 0
	s_nop 0
	s_nop 0
	s_nop 0
	s_lshr_b32 s2, s10, 5
	s_and_b32 s3, s2, 7
	s_lshr_b32 s2, s2, 3
	s_lshl_b32 s2, s2, 12
	s_add_i32 s2, s2, 2048
	s_and_b32 s11, s10, 31
	s_lshl_b32 s11, s11, 6
	s_add_i32 s2, s2, s11
	s_lshl_b32 s2, s2, 3
	s_add_i32 s2, s2, s3
	s_lshl_b32 s2, s2, 8
	s_add_u32 s4, s82, s2
	s_addc_u32 s5, s83, 0
	s_add_u32 s6, s78, s2
	s_addc_u32 s7, s79, 0
	s_add_u32 s6, s6, 0x19600000
	s_addc_u32 s7, s7, 0
	s_mov_b64 s[12:13], s[4:5]
	s_mov_b64 s[14:15], s[6:7]
	global_load_dwordx4 v[16:19], v13, s[12:13]
	global_load_dwordx4 v[32:35], v13, s[14:15]
	s_add_u32 s12, s12, 0x8000
	s_addc_u32 s13, s13, 0
	s_add_u32 s14, s14, 0x8000
	s_addc_u32 s15, s15, 0
	global_load_dwordx4 v[20:23], v13, s[12:13]
	global_load_dwordx4 v[36:39], v13, s[14:15]
	s_add_u32 s12, s12, 0x8000
	s_addc_u32 s13, s13, 0
	s_add_u32 s14, s14, 0x8000
	s_addc_u32 s15, s15, 0
	global_load_dwordx4 v[24:27], v13, s[12:13]
	global_load_dwordx4 v[40:43], v13, s[14:15]
	s_add_u32 s12, s12, 0x8000
	s_addc_u32 s13, s13, 0
	s_add_u32 s14, s14, 0x8000
	s_addc_u32 s15, s15, 0
	global_load_dwordx4 v[28:31], v13, s[12:13]
	global_load_dwordx4 v[44:47], v13, s[14:15]
	s_mov_b64 s[12:13], s[4:5]
	s_waitcnt vmcnt(6)
	v_lshlrev_b32_e32 v48, 16, v16
	v_and_b32_e32 v49, 0xffff0000, v16
	v_lshlrev_b32_e32 v50, 16, v17
	v_and_b32_e32 v51, 0xffff0000, v17
	v_lshlrev_b32_e32 v52, 16, v18
	v_and_b32_e32 v53, 0xffff0000, v18
	v_lshlrev_b32_e32 v54, 16, v19
	v_and_b32_e32 v55, 0xffff0000, v19
	v_mul_f32_e32 v56, v48, v48
	v_mul_f32_e32 v57, v49, v49
	v_add_f32_e32 v56, v56, v57
	v_mul_f32_e32 v57, v50, v50
	v_add_f32_e32 v56, v57, v56
	v_mul_f32_e32 v57, v51, v51
	v_add_f32_e32 v56, v57, v56
	v_mul_f32_e32 v57, v52, v52
	v_add_f32_e32 v56, v57, v56
	v_mul_f32_e32 v57, v53, v53
	v_add_f32_e32 v56, v57, v56
	v_mul_f32_e32 v57, v54, v54
	v_add_f32_e32 v56, v57, v56
	v_mul_f32_e32 v57, v55, v55
	v_add_f32_e32 v56, v57, v56
	s_nop 1
	v_add_f32_dpp v56, v56, v56 quad_perm:[1,0,3,2] row_mask:0xf bank_mask:0xf
	s_nop 1
	v_add_f32_dpp v56, v56, v56 quad_perm:[2,3,0,1] row_mask:0xf bank_mask:0xf
	s_nop 1
	v_add_f32_dpp v56, v56, v56 row_half_mirror row_mask:0xf bank_mask:0xf
	s_nop 1
	v_add_f32_dpp v56, v56, v56 row_mirror row_mask:0xf bank_mask:0xf
	v_fmamk_f32 v56, v56, 0x3c000000, v206
	v_mul_f32_e32 v57, 0x4b800000, v56
	v_cmp_gt_f32_e32 vcc, s51, v56
	s_nop 1
	v_cndmask_b32_e32 v56, v56, v57, vcc
	v_rsq_f32_e32 v56, v56
	s_nop 0
	v_mul_f32_e32 v57, 0x45800000, v56
	v_cndmask_b32_e32 v56, v56, v57, vcc
	v_lshlrev_b32_e32 v58, 16, v32
	v_and_b32_e32 v59, 0xffff0000, v32
	v_lshlrev_b32_e32 v60, 16, v33
	v_and_b32_e32 v61, 0xffff0000, v33
	v_lshlrev_b32_e32 v62, 16, v34
	v_and_b32_e32 v63, 0xffff0000, v34
	v_lshlrev_b32_e32 v64, 16, v35
	v_and_b32_e32 v65, 0xffff0000, v35
	v_mul_f32_e32 v66, 0xbfb8aa3b, v58
	v_mul_f32_e32 v67, 0xbfb8aa3b, v59
	v_mul_f32_e32 v68, 0xbfb8aa3b, v60
	v_mul_f32_e32 v69, 0xbfb8aa3b, v61
	v_mul_f32_e32 v70, 0xbfb8aa3b, v62
	v_mul_f32_e32 v71, 0xbfb8aa3b, v63
	v_mul_f32_e32 v72, 0xbfb8aa3b, v64
	v_mul_f32_e32 v73, 0xbfb8aa3b, v65
	v_exp_f32_e32 v66, v66
	v_exp_f32_e32 v67, v67
	v_exp_f32_e32 v68, v68
	v_exp_f32_e32 v69, v69
	v_exp_f32_e32 v70, v70
	v_exp_f32_e32 v71, v71
	v_exp_f32_e32 v72, v72
	v_exp_f32_e32 v73, v73
	v_add_f32_e32 v66, 1.0, v66
	v_add_f32_e32 v67, 1.0, v67
	v_add_f32_e32 v68, 1.0, v68
	v_add_f32_e32 v69, 1.0, v69
	v_add_f32_e32 v70, 1.0, v70
	v_add_f32_e32 v71, 1.0, v71
	v_add_f32_e32 v72, 1.0, v72
	v_add_f32_e32 v73, 1.0, v73
	v_rcp_f32_e32 v66, v66
	v_rcp_f32_e32 v67, v67
	v_rcp_f32_e32 v68, v68
	v_rcp_f32_e32 v69, v69
	v_rcp_f32_e32 v70, v70
	v_rcp_f32_e32 v71, v71
	v_rcp_f32_e32 v72, v72
	v_rcp_f32_e32 v73, v73
	v_mul_f32_e32 v66, v66, v58
	v_mul_f32_e32 v67, v67, v59
	v_mul_f32_e32 v68, v68, v60
	v_mul_f32_e32 v69, v69, v61
	v_mul_f32_e32 v70, v70, v62
	v_mul_f32_e32 v71, v71, v63
	v_mul_f32_e32 v72, v72, v64
	v_mul_f32_e32 v73, v73, v65
	v_mul_f32_e32 v48, v56, v48
	v_mul_f32_e32 v49, v56, v49
	v_mul_f32_e32 v50, v56, v50
	v_mul_f32_e32 v51, v56, v51
	v_mul_f32_e32 v52, v56, v52
	v_mul_f32_e32 v53, v56, v53
	v_mul_f32_e32 v54, v56, v54
	v_mul_f32_e32 v55, v56, v55
	v_mul_f32_e32 v48, v2, v48
	v_mul_f32_e32 v49, v3, v49
	v_mul_f32_e32 v50, v4, v50
	v_mul_f32_e32 v51, v5, v51
	v_mul_f32_e32 v52, v6, v52
	v_mul_f32_e32 v53, v7, v53
	v_mul_f32_e32 v54, v8, v54
	v_mul_f32_e32 v55, v9, v55
	v_mul_f32_e32 v48, v66, v48
	v_mul_f32_e32 v49, v67, v49
	v_mul_f32_e32 v50, v68, v50
	v_mul_f32_e32 v51, v69, v51
	v_mul_f32_e32 v52, v70, v52
	v_mul_f32_e32 v53, v71, v53
	v_mul_f32_e32 v54, v72, v54
	v_mul_f32_e32 v55, v73, v55
	v_cvt_pk_bf16_f32 v16, v48, v49
	v_cvt_pk_bf16_f32 v17, v50, v51
	v_cvt_pk_bf16_f32 v18, v52, v53
	v_cvt_pk_bf16_f32 v19, v54, v55
	global_store_dwordx4 v13, v[16:19], s[12:13]
	s_waitcnt vmcnt(5)
; DI float shx(float v, int m) { return __int_as_float(__builtin_amdgcn_ds_bpermute((lane_now() ^ m) << 2, __float_as_int(v))); }
; DI int shx(int v, int m) { return __builtin_amdgcn_ds_bpermute((lane_now() ^ m) << 2, v); }
; DI u16 f2bf(float x) { return (u16)(pk2bf(x, 0.f) & 0xffffu); }
; DI float bfs(short v) { return __uint_as_float(((unsigned)(u16)v) << 16); }
; DI void phase_outnorm_c(int wv_, int vb_, int nvb_, char* ws_, const Ctx& p) {
;     ...
;     for (int q = 0; q < 4; ++q) {
;       float f[8]; float ss = 0.f;
; #pragma unroll
;       for (int j = 0; j < 8; ++j) { f[j] = bfs(ov[q][j]); ss += f[j] * f[j]; }
;       ss += shx(ss, 1); ss += shx(ss, 2); ss += shx(ss, 4); ss += shx(ss, 8);
;       const float rn = rsqrtf(ss * (1.0f / 128.0f) + 1e-6f);
;       bf16x8 o;
; #pragma unroll
;       for (int j = 0; j < 8; ++j) { float gt = bfs(gv[q][j]); float sl = gt * __builtin_amdgcn_rcpf(1.0f + __expf(-gt)); o[j] = (short)f2bf(f[j] * rn * og[j] * sl); }
;       if (ok[q]) *(bf16x8*)(O + ((idx0 + q * stride) >> 4) * 128 + e * 8) = o;
;     }
	v_lshlrev_b32_e32 v48, 16, v20
	v_and_b32_e32 v49, 0xffff0000, v20
	v_lshlrev_b32_e32 v50, 16, v21
	v_and_b32_e32 v51, 0xffff0000, v21
	v_lshlrev_b32_e32 v52, 16, v22
	v_and_b32_e32 v53, 0xffff0000, v22
	v_lshlrev_b32_e32 v54, 16, v23
	v_and_b32_e32 v55, 0xffff0000, v23
	v_mul_f32_e32 v56, v48, v48
	v_mul_f32_e32 v57, v49, v49
	v_add_f32_e32 v56, v56, v57
	v_mul_f32_e32 v57, v50, v50
	v_add_f32_e32 v56, v57, v56
	v_mul_f32_e32 v57, v51, v51
	v_add_f32_e32 v56, v57, v56
	v_mul_f32_e32 v57, v52, v52
	v_add_f32_e32 v56, v57, v56
	v_mul_f32_e32 v57, v53, v53
	v_add_f32_e32 v56, v57, v56
	v_mul_f32_e32 v57, v54, v54
	v_add_f32_e32 v56, v57, v56
	v_mul_f32_e32 v57, v55, v55
	v_add_f32_e32 v56, v57, v56
	s_nop 1
	v_add_f32_dpp v56, v56, v56 quad_perm:[1,0,3,2] row_mask:0xf bank_mask:0xf
	s_nop 1
	v_add_f32_dpp v56, v56, v56 quad_perm:[2,3,0,1] row_mask:0xf bank_mask:0xf
	s_nop 1
	v_add_f32_dpp v56, v56, v56 row_half_mirror row_mask:0xf bank_mask:0xf
	s_nop 1
	v_add_f32_dpp v56, v56, v56 row_mirror row_mask:0xf bank_mask:0xf
	v_fmamk_f32 v56, v56, 0x3c000000, v206
	v_mul_f32_e32 v57, 0x4b800000, v56
	v_cmp_gt_f32_e32 vcc, s51, v56
	s_nop 1
	v_cndmask_b32_e32 v56, v56, v57, vcc
	v_rsq_f32_e32 v56, v56
	s_nop 0
	v_mul_f32_e32 v57, 0x45800000, v56
	v_cndmask_b32_e32 v56, v56, v57, vcc
	v_lshlrev_b32_e32 v58, 16, v36
	v_and_b32_e32 v59, 0xffff0000, v36
	v_lshlrev_b32_e32 v60, 16, v37
	v_and_b32_e32 v61, 0xffff0000, v37
	v_lshlrev_b32_e32 v62, 16, v38
	v_and_b32_e32 v63, 0xffff0000, v38
	v_lshlrev_b32_e32 v64, 16, v39
	v_and_b32_e32 v65, 0xffff0000, v39
	v_mul_f32_e32 v66, 0xbfb8aa3b, v58
	v_mul_f32_e32 v67, 0xbfb8aa3b, v59
	v_mul_f32_e32 v68, 0xbfb8aa3b, v60
	v_mul_f32_e32 v69, 0xbfb8aa3b, v61
	v_mul_f32_e32 v70, 0xbfb8aa3b, v62
	v_mul_f32_e32 v71, 0xbfb8aa3b, v63
	v_mul_f32_e32 v72, 0xbfb8aa3b, v64
	v_mul_f32_e32 v73, 0xbfb8aa3b, v65
	v_exp_f32_e32 v66, v66
	v_exp_f32_e32 v67, v67
	v_exp_f32_e32 v68, v68
	v_exp_f32_e32 v69, v69
	v_exp_f32_e32 v70, v70
	v_exp_f32_e32 v71, v71
	v_exp_f32_e32 v72, v72
	v_exp_f32_e32 v73, v73
	v_add_f32_e32 v66, 1.0, v66
	v_add_f32_e32 v67, 1.0, v67
	v_add_f32_e32 v68, 1.0, v68
	v_add_f32_e32 v69, 1.0, v69
	v_add_f32_e32 v70, 1.0, v70
	v_add_f32_e32 v71, 1.0, v71
	v_add_f32_e32 v72, 1.0, v72
	v_add_f32_e32 v73, 1.0, v73
	v_rcp_f32_e32 v66, v66
	v_rcp_f32_e32 v67, v67
	v_rcp_f32_e32 v68, v68
	v_rcp_f32_e32 v69, v69
	v_rcp_f32_e32 v70, v70
	v_rcp_f32_e32 v71, v71
	v_rcp_f32_e32 v72, v72
	v_rcp_f32_e32 v73, v73
	v_mul_f32_e32 v66, v66, v58
	v_mul_f32_e32 v67, v67, v59
	v_mul_f32_e32 v68, v68, v60
	v_mul_f32_e32 v69, v69, v61
	v_mul_f32_e32 v70, v70, v62
	v_mul_f32_e32 v71, v71, v63
	v_mul_f32_e32 v72, v72, v64
	v_mul_f32_e32 v73, v73, v65
	v_mul_f32_e32 v48, v56, v48
	v_mul_f32_e32 v49, v56, v49
	v_mul_f32_e32 v50, v56, v50
	v_mul_f32_e32 v51, v56, v51
	v_mul_f32_e32 v52, v56, v52
	v_mul_f32_e32 v53, v56, v53
	v_mul_f32_e32 v54, v56, v54
	v_mul_f32_e32 v55, v56, v55
	v_mul_f32_e32 v48, v2, v48
	v_mul_f32_e32 v49, v3, v49
	v_mul_f32_e32 v50, v4, v50
	v_mul_f32_e32 v51, v5, v51
	v_mul_f32_e32 v52, v6, v52
	v_mul_f32_e32 v53, v7, v53
	v_mul_f32_e32 v54, v8, v54
	v_mul_f32_e32 v55, v9, v55
	v_mul_f32_e32 v48, v66, v48
	v_mul_f32_e32 v49, v67, v49
	v_mul_f32_e32 v50, v68, v50
	v_mul_f32_e32 v51, v69, v51
	v_mul_f32_e32 v52, v70, v52
	v_mul_f32_e32 v53, v71, v53
	v_mul_f32_e32 v54, v72, v54
	v_mul_f32_e32 v55, v73, v55
	v_cvt_pk_bf16_f32 v20, v48, v49
	v_cvt_pk_bf16_f32 v21, v50, v51
	v_cvt_pk_bf16_f32 v22, v52, v53
	v_cvt_pk_bf16_f32 v23, v54, v55
	s_add_u32 s12, s12, 0x8000
	s_addc_u32 s13, s13, 0
	global_store_dwordx4 v13, v[20:23], s[12:13]
	s_waitcnt vmcnt(4)
	v_lshlrev_b32_e32 v48, 16, v24
	v_and_b32_e32 v49, 0xffff0000, v24
	v_lshlrev_b32_e32 v50, 16, v25
	v_and_b32_e32 v51, 0xffff0000, v25
	v_lshlrev_b32_e32 v52, 16, v26
	v_and_b32_e32 v53, 0xffff0000, v26
	v_lshlrev_b32_e32 v54, 16, v27
	v_and_b32_e32 v55, 0xffff0000, v27
	v_mul_f32_e32 v56, v48, v48
	v_mul_f32_e32 v57, v49, v49
	v_add_f32_e32 v56, v56, v57
	v_mul_f32_e32 v57, v50, v50
	v_add_f32_e32 v56, v57, v56
	v_mul_f32_e32 v57, v51, v51
	v_add_f32_e32 v56, v57, v56
	v_mul_f32_e32 v57, v52, v52
	v_add_f32_e32 v56, v57, v56
	v_mul_f32_e32 v57, v53, v53
	v_add_f32_e32 v56, v57, v56
	v_mul_f32_e32 v57, v54, v54
	v_add_f32_e32 v56, v57, v56
	v_mul_f32_e32 v57, v55, v55
	v_add_f32_e32 v56, v57, v56
	s_nop 1
	v_add_f32_dpp v56, v56, v56 quad_perm:[1,0,3,2] row_mask:0xf bank_mask:0xf
	s_nop 1
	v_add_f32_dpp v56, v56, v56 quad_perm:[2,3,0,1] row_mask:0xf bank_mask:0xf
	s_nop 1
	v_add_f32_dpp v56, v56, v56 row_half_mirror row_mask:0xf bank_mask:0xf
	s_nop 1
	v_add_f32_dpp v56, v56, v56 row_mirror row_mask:0xf bank_mask:0xf
	v_fmamk_f32 v56, v56, 0x3c000000, v206
	v_mul_f32_e32 v57, 0x4b800000, v56
	v_cmp_gt_f32_e32 vcc, s51, v56
	s_nop 1
	v_cndmask_b32_e32 v56, v56, v57, vcc
	v_rsq_f32_e32 v56, v56
	s_nop 0
	v_mul_f32_e32 v57, 0x45800000, v56
	v_cndmask_b32_e32 v56, v56, v57, vcc
	v_lshlrev_b32_e32 v58, 16, v40
	v_and_b32_e32 v59, 0xffff0000, v40
	v_lshlrev_b32_e32 v60, 16, v41
	v_and_b32_e32 v61, 0xffff0000, v41
	v_lshlrev_b32_e32 v62, 16, v42
	v_and_b32_e32 v63, 0xffff0000, v42
	v_lshlrev_b32_e32 v64, 16, v43
	v_and_b32_e32 v65, 0xffff0000, v43
	v_mul_f32_e32 v66, 0xbfb8aa3b, v58
	v_mul_f32_e32 v67, 0xbfb8aa3b, v59
	v_mul_f32_e32 v68, 0xbfb8aa3b, v60
	v_mul_f32_e32 v69, 0xbfb8aa3b, v61
	v_mul_f32_e32 v70, 0xbfb8aa3b, v62
	v_mul_f32_e32 v71, 0xbfb8aa3b, v63
	v_mul_f32_e32 v72, 0xbfb8aa3b, v64
	v_mul_f32_e32 v73, 0xbfb8aa3b, v65
	v_exp_f32_e32 v66, v66
	v_exp_f32_e32 v67, v67
	v_exp_f32_e32 v68, v68
	v_exp_f32_e32 v69, v69
	v_exp_f32_e32 v70, v70
	v_exp_f32_e32 v71, v71
; DI float shx(float v, int m) { return __int_as_float(__builtin_amdgcn_ds_bpermute((lane_now() ^ m) << 2, __float_as_int(v))); }
; DI int shx(int v, int m) { return __builtin_amdgcn_ds_bpermute((lane_now() ^ m) << 2, v); }
; DI u16 f2bf(float x) { return (u16)(pk2bf(x, 0.f) & 0xffffu); }
; DI float bfs(short v) { return __uint_as_float(((unsigned)(u16)v) << 16); }
; DI void phase_outnorm_c(int wv_, int vb_, int nvb_, char* ws_, const Ctx& p) {
;     ...
;     for (int q = 0; q < 4; ++q) {
;       float f[8]; float ss = 0.f;
; #pragma unroll
;       for (int j = 0; j < 8; ++j) { f[j] = bfs(ov[q][j]); ss += f[j] * f[j]; }
;       ss += shx(ss, 1); ss += shx(ss, 2); ss += shx(ss, 4); ss += shx(ss, 8);
;       const float rn = rsqrtf(ss * (1.0f / 128.0f) + 1e-6f);
;       bf16x8 o;
; #pragma unroll
;       for (int j = 0; j < 8; ++j) { float gt = bfs(gv[q][j]); float sl = gt * __builtin_amdgcn_rcpf(1.0f + __expf(-gt)); o[j] = (short)f2bf(f[j] * rn * og[j] * sl); }
;       if (ok[q]) *(bf16x8*)(O + ((idx0 + q * stride) >> 4) * 128 + e * 8) = o;
;     }
	v_exp_f32_e32 v72, v72
	v_exp_f32_e32 v73, v73
	v_add_f32_e32 v66, 1.0, v66
	v_add_f32_e32 v67, 1.0, v67
	v_add_f32_e32 v68, 1.0, v68
	v_add_f32_e32 v69, 1.0, v69
	v_add_f32_e32 v70, 1.0, v70
	v_add_f32_e32 v71, 1.0, v71
	v_add_f32_e32 v72, 1.0, v72
	v_add_f32_e32 v73, 1.0, v73
	v_rcp_f32_e32 v66, v66
	v_rcp_f32_e32 v67, v67
	v_rcp_f32_e32 v68, v68
	v_rcp_f32_e32 v69, v69
	v_rcp_f32_e32 v70, v70
	v_rcp_f32_e32 v71, v71
	v_rcp_f32_e32 v72, v72
	v_rcp_f32_e32 v73, v73
	v_mul_f32_e32 v66, v66, v58
	v_mul_f32_e32 v67, v67, v59
	v_mul_f32_e32 v68, v68, v60
	v_mul_f32_e32 v69, v69, v61
	v_mul_f32_e32 v70, v70, v62
	v_mul_f32_e32 v71, v71, v63
	v_mul_f32_e32 v72, v72, v64
	v_mul_f32_e32 v73, v73, v65
	v_mul_f32_e32 v48, v56, v48
	v_mul_f32_e32 v49, v56, v49
	v_mul_f32_e32 v50, v56, v50
	v_mul_f32_e32 v51, v56, v51
	v_mul_f32_e32 v52, v56, v52
	v_mul_f32_e32 v53, v56, v53
	v_mul_f32_e32 v54, v56, v54
	v_mul_f32_e32 v55, v56, v55
	v_mul_f32_e32 v48, v2, v48
	v_mul_f32_e32 v49, v3, v49
	v_mul_f32_e32 v50, v4, v50
	v_mul_f32_e32 v51, v5, v51
	v_mul_f32_e32 v52, v6, v52
	v_mul_f32_e32 v53, v7, v53
	v_mul_f32_e32 v54, v8, v54
	v_mul_f32_e32 v55, v9, v55
	v_mul_f32_e32 v48, v66, v48
	v_mul_f32_e32 v49, v67, v49
	v_mul_f32_e32 v50, v68, v50
	v_mul_f32_e32 v51, v69, v51
	v_mul_f32_e32 v52, v70, v52
	v_mul_f32_e32 v53, v71, v53
	v_mul_f32_e32 v54, v72, v54
	v_mul_f32_e32 v55, v73, v55
	v_cvt_pk_bf16_f32 v24, v48, v49
	v_cvt_pk_bf16_f32 v25, v50, v51
	v_cvt_pk_bf16_f32 v26, v52, v53
	v_cvt_pk_bf16_f32 v27, v54, v55
	s_add_u32 s12, s12, 0x8000
	s_addc_u32 s13, s13, 0
	global_store_dwordx4 v13, v[24:27], s[12:13]
	s_waitcnt vmcnt(3)
	v_lshlrev_b32_e32 v48, 16, v28
	v_and_b32_e32 v49, 0xffff0000, v28
	v_lshlrev_b32_e32 v50, 16, v29
	v_and_b32_e32 v51, 0xffff0000, v29
	v_lshlrev_b32_e32 v52, 16, v30
	v_and_b32_e32 v53, 0xffff0000, v30
	v_lshlrev_b32_e32 v54, 16, v31
	v_and_b32_e32 v55, 0xffff0000, v31
	v_mul_f32_e32 v56, v48, v48
	v_mul_f32_e32 v57, v49, v49
	v_add_f32_e32 v56, v56, v57
	v_mul_f32_e32 v57, v50, v50
	v_add_f32_e32 v56, v57, v56
	v_mul_f32_e32 v57, v51, v51
	v_add_f32_e32 v56, v57, v56
	v_mul_f32_e32 v57, v52, v52
	v_add_f32_e32 v56, v57, v56
	v_mul_f32_e32 v57, v53, v53
	v_add_f32_e32 v56, v57, v56
	v_mul_f32_e32 v57, v54, v54
	v_add_f32_e32 v56, v57, v56
	v_mul_f32_e32 v57, v55, v55
	v_add_f32_e32 v56, v57, v56
	s_nop 1
	v_add_f32_dpp v56, v56, v56 quad_perm:[1,0,3,2] row_mask:0xf bank_mask:0xf
	s_nop 1
	v_add_f32_dpp v56, v56, v56 quad_perm:[2,3,0,1] row_mask:0xf bank_mask:0xf
	s_nop 1
	v_add_f32_dpp v56, v56, v56 row_half_mirror row_mask:0xf bank_mask:0xf
	s_nop 1
	v_add_f32_dpp v56, v56, v56 row_mirror row_mask:0xf bank_mask:0xf
	v_fmamk_f32 v56, v56, 0x3c000000, v206
	v_mul_f32_e32 v57, 0x4b800000, v56
	v_cmp_gt_f32_e32 vcc, s51, v56
	s_nop 1
	v_cndmask_b32_e32 v56, v56, v57, vcc
	v_rsq_f32_e32 v56, v56
	s_nop 0
	v_mul_f32_e32 v57, 0x45800000, v56
	v_cndmask_b32_e32 v56, v56, v57, vcc
	v_lshlrev_b32_e32 v58, 16, v44
	v_and_b32_e32 v59, 0xffff0000, v44
	v_lshlrev_b32_e32 v60, 16, v45
	v_and_b32_e32 v61, 0xffff0000, v45
	v_lshlrev_b32_e32 v62, 16, v46
	v_and_b32_e32 v63, 0xffff0000, v46
	v_lshlrev_b32_e32 v64, 16, v47
	v_and_b32_e32 v65, 0xffff0000, v47
	v_mul_f32_e32 v66, 0xbfb8aa3b, v58
	v_mul_f32_e32 v67, 0xbfb8aa3b, v59
	v_mul_f32_e32 v68, 0xbfb8aa3b, v60
	v_mul_f32_e32 v69, 0xbfb8aa3b, v61
	v_mul_f32_e32 v70, 0xbfb8aa3b, v62
	v_mul_f32_e32 v71, 0xbfb8aa3b, v63
	v_mul_f32_e32 v72, 0xbfb8aa3b, v64
	v_mul_f32_e32 v73, 0xbfb8aa3b, v65
	v_exp_f32_e32 v66, v66
	v_exp_f32_e32 v67, v67
	v_exp_f32_e32 v68, v68
	v_exp_f32_e32 v69, v69
	v_exp_f32_e32 v70, v70
	v_exp_f32_e32 v71, v71
	v_exp_f32_e32 v72, v72
	v_exp_f32_e32 v73, v73
	v_add_f32_e32 v66, 1.0, v66
	v_add_f32_e32 v67, 1.0, v67
	v_add_f32_e32 v68, 1.0, v68
	v_add_f32_e32 v69, 1.0, v69
	v_add_f32_e32 v70, 1.0, v70
	v_add_f32_e32 v71, 1.0, v71
	v_add_f32_e32 v72, 1.0, v72
	v_add_f32_e32 v73, 1.0, v73
	v_rcp_f32_e32 v66, v66
	v_rcp_f32_e32 v67, v67
	v_rcp_f32_e32 v68, v68
	v_rcp_f32_e32 v69, v69
	v_rcp_f32_e32 v70, v70
	v_rcp_f32_e32 v71, v71
	v_rcp_f32_e32 v72, v72
	v_rcp_f32_e32 v73, v73
	v_mul_f32_e32 v66, v66, v58
	v_mul_f32_e32 v67, v67, v59
	v_mul_f32_e32 v68, v68, v60
	v_mul_f32_e32 v69, v69, v61
	v_mul_f32_e32 v70, v70, v62
	v_mul_f32_e32 v71, v71, v63
	v_mul_f32_e32 v72, v72, v64
	v_mul_f32_e32 v73, v73, v65
	v_mul_f32_e32 v48, v56, v48
	v_mul_f32_e32 v49, v56, v49
	v_mul_f32_e32 v50, v56, v50
	v_mul_f32_e32 v51, v56, v51
	v_mul_f32_e32 v52, v56, v52
	v_mul_f32_e32 v53, v56, v53
	v_mul_f32_e32 v54, v56, v54
	v_mul_f32_e32 v55, v56, v55
	v_mul_f32_e32 v48, v2, v48
	v_mul_f32_e32 v49, v3, v49
	v_mul_f32_e32 v50, v4, v50
	v_mul_f32_e32 v51, v5, v51
	v_mul_f32_e32 v52, v6, v52
	v_mul_f32_e32 v53, v7, v53
	v_mul_f32_e32 v54, v8, v54
	v_mul_f32_e32 v55, v9, v55
	v_mul_f32_e32 v48, v66, v48
	v_mul_f32_e32 v49, v67, v49
	v_mul_f32_e32 v50, v68, v50
	v_mul_f32_e32 v51, v69, v51
	v_mul_f32_e32 v52, v70, v52
	v_mul_f32_e32 v53, v71, v53
	v_mul_f32_e32 v54, v72, v54
	v_mul_f32_e32 v55, v73, v55
	v_cvt_pk_bf16_f32 v28, v48, v49
	v_cvt_pk_bf16_f32 v29, v50, v51
	v_cvt_pk_bf16_f32 v30, v52, v53
	v_cvt_pk_bf16_f32 v31, v54, v55
	s_add_u32 s12, s12, 0x8000
	s_addc_u32 s13, s13, 0
	global_store_dwordx4 v13, v[28:31], s[12:13]
	s_add_i32 s10, s10, 512
	s_cmp_lt_u32 s10, 0x800
	s_cbranch_scc1 .Lonp_loop
	s_waitcnt vmcnt(0)
	s_mov_b64 s[2:3], 0
	s_branch .LBB0_223
	s_mov_b32 s0, s33
	v_mov_b32_e32 v0, v204
	s_nop 0
	v_lshl_or_b32 v12, s0, 6, v0
	v_readlane_b32 s0, v254, 8
	v_ashrrev_i32_e32 v13, 31, v12
	v_readlane_b32 s1, v254, 9
	s_nop 1
	v_lshl_add_u64 v[10:11], s[0:1], 0, v[12:13]
	s_mov_b64 s[0:1], 0x400000
	v_cmp_gt_u64_e32 vcc, s[0:1], v[10:11]
	s_and_saveexec_b64 s[8:9], vcc
	s_cbranch_execz .LBB0_222
	v_lshlrev_b32_e32 v0, 3, v0
	v_and_b32_e32 v0, 0x78, v0
	v_lshlrev_b32_e32 v6, 2, v0
	global_load_dwordx4 v[2:5], v6, s[14:15] offset:16
	s_nop 0
	global_load_dwordx4 v[6:9], v6, s[14:15]
	v_lshlrev_b32_e32 v0, 1, v0
	v_lshl_add_u64 v[14:15], s[78:79], 0, v[0:1]
	s_mov_b64 s[0:1], 0x19600000
	v_lshl_add_u64 v[32:33], v[14:15], 0, s[0:1]
	v_readlane_b32 s0, v253, 38
	v_readlane_b32 s1, v253, 39
	v_lshl_add_u64 v[30:31], s[82:83], 0, v[0:1]
	s_mov_b64 s[10:11], 0
	v_lshl_add_u64 v[34:35], v[12:13], 3, s[0:1]
	s_branch .LBB0_216

; DI u16 f2bf(float x) { return (u16)(pk2bf(x, 0.f) & 0xffffu); }
; #define CVT_LOAD(C, V) { _Pragma("unroll") for (int i = 0; i < 4; ++i) { const int n_ = (C).n0 + tx * 4; \
;     V[i] = (n_ < (C).N) ? *(const float4*)((C).src + (size_t)((C).k0 + ty + 16 * i) * (C).N + n_) : make_float4(0.f, 0.f, 0.f, 0.f); } }
; DI void phase_convert(int wv_, int vb_, int nvb_, char* ws_, const Ctx& p, char* smem) {
;     ...
;   CvtTile cur = cvt_locate(p, (vb_ < total) ? vb_ : total - 1);
;   float4 v[4];
;   CVT_LOAD(cur, v)
;   for (int k_ = 0; k_ < trips_; ++k_) {
;     const int tn = vb_ + (k_ + 1) * nvb_;
;     const CvtTile nxt = cvt_locate(p, (tn < total) ? tn : total - 1);
;     float4 vn[4];
;     CVT_LOAD(nxt, vn)
; #pragma unroll
;     for (int i = 0; i < 4; ++i) { float* d = tile + (ty + 16 * i) * 65 + tx * 4; d[0] = v[i].x; d[1] = v[i].y; d[2] = v[i].z; d[3] = v[i].w; }
;     __syncthreads();
;     {
;       const int n = tid >> 2, kq = tid & 3;
;       bf16x8 o0, o1;
; #pragma unroll
;       for (int j = 0; j < 8; ++j) { o0[j] = (short)f2bf(tile[(kq * 16 + j) * 65 + n]); o1[j] = (short)f2bf(tile[(kq * 16 + 8 + j) * 65 + n]); }
;       u16* dst = (u16*)(ws_ + WS_WT) + (size_t)cur.off + (size_t)(cur.n0 + n) * cur.K + cur.k0 + kq * 16;
;       *(bf16x8*)dst = o0; *(bf16x8*)(dst + 8) = o1;
;     }
;     __syncthreads();
;     cur = nxt;
; #pragma unroll
;     for (int i = 0; i < 4; ++i) v[i] = vn[i];
;   }
; DI void phase_outnorm_c(int wv_, int vb_, int nvb_, char* ws_, const Ctx& p) {
;     ...
;   const int tid = tidx(wv_); const int e = tid & 15;
;   float og[8];
; #pragma unroll
;   for (int j = 0; j < 8; ++j) og[j] = p.c_o_gain[e * 8 + j];
.Lcvt_late_chk:
	s_nop 0
	s_nop 0
	s_nop 0
	s_nop 0
	s_nop 0
	s_nop 0
	s_nop 0
	s_nop 0
	s_nop 0
	s_nop 0
	s_nop 0
	s_nop 0
	s_nop 0
	s_nop 0
	s_nop 0
	s_nop 0
	s_nop 0
	s_nop 0
	s_nop 0
	s_nop 0
	s_nop 0
	s_nop 0
	s_nop 0
	s_nop 0
	s_nop 0
	s_nop 0
	s_nop 0
	s_nop 0
	s_nop 0
	v_readlane_b32 s0, v254, 14
	s_cmp_lt_u32 s0, 0x80
	s_cbranch_scc1 .LBB0_235
	s_mov_b64 s[56:57], s[54:55]
	v_readlane_b32 s54, v254, 46
	v_readlane_b32 s55, v254, 47
	v_readlane_b32 s44, v254, 14
	v_readlane_b32 s35, v254, 56
	s_sub_i32 s44, s44, 128
	s_sub_i32 s35, s35, 128
	s_mov_b32 s10, s33
	v_lshl_add_u32 v81, s10, 6, v204
	v_lshrrev_b32_e32 v74, 4, v81
	v_and_b32_e32 v75, 15, v81
	v_lshlrev_b32_e32 v75, 2, v75
	v_lshrrev_b32_e32 v78, 2, v81
	v_and_b32_e32 v79, 3, v81
	v_mul_u32_u24_e32 v76, 65, v74
	v_add_u32_e32 v76, v76, v75
	v_lshl_add_u32 v76, v76, 2, v214
	v_mul_u32_u24_e32 v77, 0x410, v79
	v_add_u32_e32 v77, v77, v78
	v_lshl_add_u32 v77, v77, 2, v214
	v_lshlrev_b32_e32 v79, 5, v79
	s_mov_b32 s34, 0
.Lcvtb_loop:
	s_mul_i32 s52, s34, s35
	s_add_i32 s52, s52, s44
	s_min_u32 s52, s52, 0x15ff
	s_mov_b32 s0, 4
	s_mov_b32 s1, 0x1200
	s_mov_b32 s2, 0
	s_mov_b32 s3, 0x480000
	s_mov_b32 s7, 0x480000
	s_mov_b32 s11, 0
	s_cmp_ge_u32 s52, 0x480
	s_cselect_b32 s0, 3, s0
	s_cselect_b32 s1, 0x400, s1
	s_cselect_b32 s2, 1, s2
	s_cselect_b32 s3, 0x80000, s3
	s_cselect_b32 s7, 0x980000, s7
	s_cselect_b32 s11, 0x480, s11
	s_cmp_ge_u32 s52, 0x500
	s_cselect_b32 s0, 4, s0
	s_cselect_b32 s1, 0x400, s1
	s_cselect_b32 s2, 5, s2
	s_cselect_b32 s3, 0, s3
	s_cselect_b32 s7, 0x1180000, s7
	s_cselect_b32 s11, 0x500, s11
	s_cmp_ge_u32 s52, 0x600
	s_cselect_b32 s0, 4, s0
	s_cselect_b32 s1, 0x1000, s1
	s_cselect_b32 s2, 6, s2
	s_cselect_b32 s3, 0x800000, s3
	s_cselect_b32 s7, 0x1a80000, s7
	s_cselect_b32 s11, 0x600, s11
	s_cmp_ge_u32 s52, 0xa00
	s_cselect_b32 s0, 4, s0
	s_cselect_b32 s1, 0x1000, s1
	s_cselect_b32 s2, 6, s2
	s_cselect_b32 s3, 0xc00000, s3
	s_cselect_b32 s7, 0x1e80000, s7
	s_cselect_b32 s11, 0xa00, s11
	s_cmp_ge_u32 s52, 0xe00
	s_cselect_b32 s0, 6, s0
	s_cselect_b32 s1, 0x400, s1
	s_cselect_b32 s2, 7, s2
	s_cselect_b32 s3, 0x800000, s3
	s_cselect_b32 s7, 0x2a80000, s7
	s_cselect_b32 s11, 0xe00, s11
	s_cmp_ge_u32 s52, 0x1200
	s_cselect_b32 s0, 6, s0
	s_cselect_b32 s1, 0x400, s1
	s_cselect_b32 s2, 7, s2
	s_cselect_b32 s3, 0xc00000, s3
	s_cselect_b32 s7, 0x2e80000, s7
	s_cselect_b32 s11, 0x1200, s11
	s_lshl_b32 s15, s2, 3
	s_add_i32 s15, s15, 0x60
	s_load_dwordx2 s[18:19], s[54:55], s15
	s_sub_i32 s15, s52, s11
	s_lshl_b32 s2, 1, s0
	s_add_i32 s2, s2, -1
	s_and_b32 s2, s15, s2
	s_lshl_b32 s2, s2, 6
	s_lshr_b32 s15, s15, s0
	s_lshl_b32 s15, s15, 6
	s_mov_b32 s6, s0
	s_add_i32 s11, s0, 6
	s_lshl_b32 s11, s15, s11
	s_add_i32 s11, s11, s7
	s_add_i32 s11, s11, s2
	s_lshl_b32 s11, s11, 1
	s_add_u32 s4, s78, s11
	s_addc_u32 s5, s79, 0
	s_mul_i32 s7, s2, s1
	s_add_i32 s7, s7, s3
	s_add_i32 s7, s7, s15
	s_lshl_b32 s7, s7, 2
	s_lshl_b32 s3, s1, 6
	v_mul_u32_u24_e32 v81, s1, v74
	v_add_u32_e32 v81, v81, v75
	v_lshlrev_b32_e32 v80, 2, v81
	v_add_u32_e32 v81, s15, v75
	v_mov_b32_e32 v2, 0
	v_mov_b32_e32 v3, 0
	v_mov_b32_e32 v4, 0
	v_mov_b32_e32 v5, 0
	v_mov_b32_e32 v6, 0
	v_mov_b32_e32 v7, 0
	v_mov_b32_e32 v8, 0
	v_mov_b32_e32 v9, 0
	v_mov_b32_e32 v10, 0
	v_mov_b32_e32 v11, 0
	v_mov_b32_e32 v12, 0
	v_mov_b32_e32 v13, 0
	v_mov_b32_e32 v14, 0
	v_mov_b32_e32 v15, 0
	v_mov_b32_e32 v16, 0
	v_mov_b32_e32 v17, 0
	s_waitcnt lgkmcnt(0)
	s_add_u32 s18, s18, s7
	s_addc_u32 s19, s19, 0
	v_cmp_gt_u32_e32 vcc, s1, v81
	s_and_saveexec_b64 s[100:101], vcc
	global_load_dwordx4 v[2:5], v80, s[18:19]
	s_add_u32 s18, s18, s3
	s_addc_u32 s19, s19, 0
	global_load_dwordx4 v[6:9], v80, s[18:19]
	s_add_u32 s18, s18, s3
	s_addc_u32 s19, s19, 0
	global_load_dwordx4 v[10:13], v80, s[18:19]
	s_add_u32 s18, s18, s3
	s_addc_u32 s19, s19, 0
	global_load_dwordx4 v[14:17], v80, s[18:19]
	s_mov_b64 exec, s[100:101]
	s_waitcnt vmcnt(0)
	ds_write_b32 v76, v2
	ds_write_b32 v76, v3 offset:4
	ds_write_b32 v76, v4 offset:8
	ds_write_b32 v76, v5 offset:12
	ds_write_b32 v76, v6 offset:4160
	ds_write_b32 v76, v7 offset:4164
	ds_write_b32 v76, v8 offset:4168
	ds_write_b32 v76, v9 offset:4172
	ds_write_b32 v76, v10 offset:8320
	ds_write_b32 v76, v11 offset:8324
	ds_write_b32 v76, v12 offset:8328
	ds_write_b32 v76, v13 offset:8332
	ds_write_b32 v76, v14 offset:12480
	ds_write_b32 v76, v15 offset:12484
	ds_write_b32 v76, v16 offset:12488
	ds_write_b32 v76, v17 offset:12492
	s_waitcnt lgkmcnt(0)
	s_barrier
	ds_read_b32 v50, v77
	ds_read_b32 v51, v77 offset:260
	ds_read_b32 v52, v77 offset:520
	ds_read_b32 v53, v77 offset:780
	ds_read_b32 v54, v77 offset:1040
	ds_read_b32 v55, v77 offset:1300
	ds_read_b32 v56, v77 offset:1560
	ds_read_b32 v57, v77 offset:1820
	ds_read_b32 v58, v77 offset:2080
	ds_read_b32 v59, v77 offset:2340
	ds_read_b32 v60, v77 offset:2600
	ds_read_b32 v61, v77 offset:2860
	ds_read_b32 v62, v77 offset:3120
	ds_read_b32 v63, v77 offset:3380
	ds_read_b32 v64, v77 offset:3640
	ds_read_b32 v65, v77 offset:3900
	s_add_i32 s15, s6, 7
	v_lshlrev_b32_e32 v82, s15, v78
	v_add_u32_e32 v82, v82, v79
	s_waitcnt lgkmcnt(0)
	v_cvt_pk_bf16_f32 v66, v50, v51
	v_cvt_pk_bf16_f32 v67, v52, v53
	v_cvt_pk_bf16_f32 v68, v54, v55
	v_cvt_pk_bf16_f32 v69, v56, v57
	v_cvt_pk_bf16_f32 v70, v58, v59
	v_cvt_pk_bf16_f32 v71, v60, v61
	v_cvt_pk_bf16_f32 v72, v62, v63
	v_cvt_pk_bf16_f32 v73, v64, v65
	global_store_dwordx4 v82, v[66:69], s[4:5]
	global_store_dwordx4 v82, v[70:73], s[4:5] offset:16
	s_barrier
	s_add_i32 s34, s34, 1
	s_mul_i32 s15, s34, s35
	s_cmp_lt_u32 s15, 0x1600
	s_cbranch_scc1 .Lcvtb_loop
	s_waitcnt vmcnt(0)
	s_mov_b64 s[54:55], s[56:57]
	v_lshl_or_b32 v10, s33, 6, v204
	v_and_b32_e32 v11, 15, v10
	v_lshrrev_b32_e32 v12, 4, v10
	v_lshlrev_b32_e32 v13, 11, v12
	v_lshl_add_u32 v13, v11, 4, v13
	v_readlane_b32 s8, v254, 28
	v_readlane_b32 s9, v254, 29
	v_lshlrev_b32_e32 v14, 5, v11
	v_readlane_b32 s10, v254, 14
	s_sub_i32 s10, s10, 128
	s_nop 4
	global_load_dwordx4 v[2:5], v14, s[8:9]
	global_load_dwordx4 v[6:9], v14, s[8:9] offset:16
; DI float shx(float v, int m) { return __int_as_float(__builtin_amdgcn_ds_bpermute((lane_now() ^ m) << 2, __float_as_int(v))); }
; DI int shx(int v, int m) { return __builtin_amdgcn_ds_bpermute((lane_now() ^ m) << 2, v); }
; DI u16 f2bf(float x) { return (u16)(pk2bf(x, 0.f) & 0xffffu); }
; DI float bfs(short v) { return __uint_as_float(((unsigned)(u16)v) << 16); }
; DI void phase_outnorm_c(int wv_, int vb_, int nvb_, char* ws_, const Ctx& p) {
;     ...
;   for (size_t idx0 = (size_t)vb_ * 256 + tid; idx0 < total; idx0 += 4 * stride) {
;     bf16x8 ov[4], gv[4]; bool ok[4];
; #pragma unroll
;     for (int q = 0; q < 4; ++q) { const size_t idx = idx0 + q * stride; ok[q] = idx < total; const size_t rowh = (ok[q] ? idx : idx0) >> 4;
;       ov[q] = *(const bf16x8*)(O + rowh * 128 + e * 8); gv[q] = *(const bf16x8*)(G + rowh * 128 + e * 8); }
; #pragma unroll
;     for (int q = 0; q < 4; ++q) {
;       float f[8]; float ss = 0.f;
; #pragma unroll
;       for (int j = 0; j < 8; ++j) { f[j] = bfs(ov[q][j]); ss += f[j] * f[j]; }
;       ss += shx(ss, 1); ss += shx(ss, 2); ss += shx(ss, 4); ss += shx(ss, 8);
;       const float rn = rsqrtf(ss * (1.0f / 128.0f) + 1e-6f);
;       bf16x8 o;
; #pragma unroll
;       for (int j = 0; j < 8; ++j) { float gt = bfs(gv[q][j]); float sl = gt * __builtin_amdgcn_rcpf(1.0f + __expf(-gt)); o[j] = (short)f2bf(f[j] * rn * og[j] * sl); }
;       if (ok[q]) *(bf16x8*)(O + ((idx0 + q * stride) >> 4) * 128 + e * 8) = o;
;     }
.Loni_loop:
	s_lshr_b32 s2, s10, 5
	s_and_b32 s3, s2, 7
	s_lshr_b32 s2, s2, 3
	s_lshl_b32 s2, s2, 12
	s_and_b32 s11, s10, 31
	s_lshl_b32 s11, s11, 6
	s_add_i32 s2, s2, s11
	s_lshl_b32 s2, s2, 3
	s_add_i32 s2, s2, s3
	s_lshl_b32 s2, s2, 8
	s_add_u32 s4, s82, s2
	s_addc_u32 s5, s83, 0
	s_add_u32 s6, s78, s2
	s_addc_u32 s7, s79, 0
	s_add_u32 s6, s6, 0x19600000
	s_addc_u32 s7, s7, 0
	s_mov_b64 s[12:13], s[4:5]
	s_mov_b64 s[14:15], s[6:7]
	global_load_dwordx4 v[16:19], v13, s[12:13]
	global_load_dwordx4 v[32:35], v13, s[14:15]
	s_add_u32 s12, s12, 0x8000
	s_addc_u32 s13, s13, 0
	s_add_u32 s14, s14, 0x8000
	s_addc_u32 s15, s15, 0
	global_load_dwordx4 v[20:23], v13, s[12:13]
	global_load_dwordx4 v[36:39], v13, s[14:15]
	s_add_u32 s12, s12, 0x8000
	s_addc_u32 s13, s13, 0
	s_add_u32 s14, s14, 0x8000
	s_addc_u32 s15, s15, 0
	global_load_dwordx4 v[24:27], v13, s[12:13]
	global_load_dwordx4 v[40:43], v13, s[14:15]
	s_add_u32 s12, s12, 0x8000
	s_addc_u32 s13, s13, 0
	s_add_u32 s14, s14, 0x8000
	s_addc_u32 s15, s15, 0
	global_load_dwordx4 v[28:31], v13, s[12:13]
	global_load_dwordx4 v[44:47], v13, s[14:15]
	s_mov_b64 s[12:13], s[4:5]
	s_waitcnt vmcnt(6)
	v_lshlrev_b32_e32 v48, 16, v16
	v_and_b32_e32 v49, 0xffff0000, v16
	v_lshlrev_b32_e32 v50, 16, v17
	v_and_b32_e32 v51, 0xffff0000, v17
	v_lshlrev_b32_e32 v52, 16, v18
	v_and_b32_e32 v53, 0xffff0000, v18
	v_lshlrev_b32_e32 v54, 16, v19
	v_and_b32_e32 v55, 0xffff0000, v19
	v_mul_f32_e32 v56, v48, v48
	v_mul_f32_e32 v57, v49, v49
	v_add_f32_e32 v56, v56, v57
	v_mul_f32_e32 v57, v50, v50
	v_add_f32_e32 v56, v57, v56
	v_mul_f32_e32 v57, v51, v51
	v_add_f32_e32 v56, v57, v56
	v_mul_f32_e32 v57, v52, v52
	v_add_f32_e32 v56, v57, v56
	v_mul_f32_e32 v57, v53, v53
	v_add_f32_e32 v56, v57, v56
	v_mul_f32_e32 v57, v54, v54
	v_add_f32_e32 v56, v57, v56
	v_mul_f32_e32 v57, v55, v55
	v_add_f32_e32 v56, v57, v56
	s_nop 1
	v_add_f32_dpp v56, v56, v56 quad_perm:[1,0,3,2] row_mask:0xf bank_mask:0xf
	s_nop 1
	v_add_f32_dpp v56, v56, v56 quad_perm:[2,3,0,1] row_mask:0xf bank_mask:0xf
	s_nop 1
	v_add_f32_dpp v56, v56, v56 row_half_mirror row_mask:0xf bank_mask:0xf
	s_nop 1
	v_add_f32_dpp v56, v56, v56 row_mirror row_mask:0xf bank_mask:0xf
	v_fmamk_f32 v56, v56, 0x3c000000, v206
	v_mul_f32_e32 v57, 0x4b800000, v56
	v_cmp_gt_f32_e32 vcc, s51, v56
	s_nop 1
	v_cndmask_b32_e32 v56, v56, v57, vcc
	v_rsq_f32_e32 v56, v56
	s_nop 0
	v_mul_f32_e32 v57, 0x45800000, v56
	v_cndmask_b32_e32 v56, v56, v57, vcc
	v_lshlrev_b32_e32 v58, 16, v32
	v_and_b32_e32 v59, 0xffff0000, v32
	v_lshlrev_b32_e32 v60, 16, v33
	v_and_b32_e32 v61, 0xffff0000, v33
	v_lshlrev_b32_e32 v62, 16, v34
	v_and_b32_e32 v63, 0xffff0000, v34
	v_lshlrev_b32_e32 v64, 16, v35
	v_and_b32_e32 v65, 0xffff0000, v35
	v_mul_f32_e32 v66, 0xbfb8aa3b, v58
	v_mul_f32_e32 v67, 0xbfb8aa3b, v59
	v_mul_f32_e32 v68, 0xbfb8aa3b, v60
	v_mul_f32_e32 v69, 0xbfb8aa3b, v61
	v_mul_f32_e32 v70, 0xbfb8aa3b, v62
	v_mul_f32_e32 v71, 0xbfb8aa3b, v63
	v_mul_f32_e32 v72, 0xbfb8aa3b, v64
	v_mul_f32_e32 v73, 0xbfb8aa3b, v65
	v_exp_f32_e32 v66, v66
	v_exp_f32_e32 v67, v67
	v_exp_f32_e32 v68, v68
	v_exp_f32_e32 v69, v69
	v_exp_f32_e32 v70, v70
	v_exp_f32_e32 v71, v71
	v_exp_f32_e32 v72, v72
	v_exp_f32_e32 v73, v73
	v_add_f32_e32 v66, 1.0, v66
	v_add_f32_e32 v67, 1.0, v67
	v_add_f32_e32 v68, 1.0, v68
	v_add_f32_e32 v69, 1.0, v69
	v_add_f32_e32 v70, 1.0, v70
	v_add_f32_e32 v71, 1.0, v71
	v_add_f32_e32 v72, 1.0, v72
	v_add_f32_e32 v73, 1.0, v73
	v_rcp_f32_e32 v66, v66
	v_rcp_f32_e32 v67, v67
	v_rcp_f32_e32 v68, v68
	v_rcp_f32_e32 v69, v69
	v_rcp_f32_e32 v70, v70
	v_rcp_f32_e32 v71, v71
	v_rcp_f32_e32 v72, v72
	v_rcp_f32_e32 v73, v73
	v_mul_f32_e32 v66, v66, v58
	v_mul_f32_e32 v67, v67, v59
	v_mul_f32_e32 v68, v68, v60
	v_mul_f32_e32 v69, v69, v61
	v_mul_f32_e32 v70, v70, v62
	v_mul_f32_e32 v71, v71, v63
	v_mul_f32_e32 v72, v72, v64
	v_mul_f32_e32 v73, v73, v65
	v_mul_f32_e32 v48, v56, v48
	v_mul_f32_e32 v49, v56, v49
	v_mul_f32_e32 v50, v56, v50
	v_mul_f32_e32 v51, v56, v51
	v_mul_f32_e32 v52, v56, v52
	v_mul_f32_e32 v53, v56, v53
	v_mul_f32_e32 v54, v56, v54
	v_mul_f32_e32 v55, v56, v55
	v_mul_f32_e32 v48, v2, v48
	v_mul_f32_e32 v49, v3, v49
	v_mul_f32_e32 v50, v4, v50
	v_mul_f32_e32 v51, v5, v51
	v_mul_f32_e32 v52, v6, v52
	v_mul_f32_e32 v53, v7, v53
	v_mul_f32_e32 v54, v8, v54
	v_mul_f32_e32 v55, v9, v55
	v_mul_f32_e32 v48, v66, v48
	v_mul_f32_e32 v49, v67, v49
	v_mul_f32_e32 v50, v68, v50
	v_mul_f32_e32 v51, v69, v51
	v_mul_f32_e32 v52, v70, v52
	v_mul_f32_e32 v53, v71, v53
	v_mul_f32_e32 v54, v72, v54
	v_mul_f32_e32 v55, v73, v55
	v_cvt_pk_bf16_f32 v16, v48, v49
	v_cvt_pk_bf16_f32 v17, v50, v51
	v_cvt_pk_bf16_f32 v18, v52, v53
	v_cvt_pk_bf16_f32 v19, v54, v55
	global_store_dwordx4 v13, v[16:19], s[12:13]
	s_waitcnt vmcnt(5)
; DI float shx(float v, int m) { return __int_as_float(__builtin_amdgcn_ds_bpermute((lane_now() ^ m) << 2, __float_as_int(v))); }
; DI int shx(int v, int m) { return __builtin_amdgcn_ds_bpermute((lane_now() ^ m) << 2, v); }
; DI u16 f2bf(float x) { return (u16)(pk2bf(x, 0.f) & 0xffffu); }
; DI float bfs(short v) { return __uint_as_float(((unsigned)(u16)v) << 16); }
; DI void phase_outnorm_c(int wv_, int vb_, int nvb_, char* ws_, const Ctx& p) {
;     ...
;     for (int q = 0; q < 4; ++q) {
;       float f[8]; float ss = 0.f;
; #pragma unroll
;       for (int j = 0; j < 8; ++j) { f[j] = bfs(ov[q][j]); ss += f[j] * f[j]; }
;       ss += shx(ss, 1); ss += shx(ss, 2); ss += shx(ss, 4); ss += shx(ss, 8);
;       const float rn = rsqrtf(ss * (1.0f / 128.0f) + 1e-6f);
;       bf16x8 o;
; #pragma unroll
;       for (int j = 0; j < 8; ++j) { float gt = bfs(gv[q][j]); float sl = gt * __builtin_amdgcn_rcpf(1.0f + __expf(-gt)); o[j] = (short)f2bf(f[j] * rn * og[j] * sl); }
;       if (ok[q]) *(bf16x8*)(O + ((idx0 + q * stride) >> 4) * 128 + e * 8) = o;
;     }
	v_lshlrev_b32_e32 v48, 16, v20
	v_and_b32_e32 v49, 0xffff0000, v20
	v_lshlrev_b32_e32 v50, 16, v21
	v_and_b32_e32 v51, 0xffff0000, v21
	v_lshlrev_b32_e32 v52, 16, v22
	v_and_b32_e32 v53, 0xffff0000, v22
	v_lshlrev_b32_e32 v54, 16, v23
	v_and_b32_e32 v55, 0xffff0000, v23
	v_mul_f32_e32 v56, v48, v48
	v_mul_f32_e32 v57, v49, v49
	v_add_f32_e32 v56, v56, v57
	v_mul_f32_e32 v57, v50, v50
	v_add_f32_e32 v56, v57, v56
	v_mul_f32_e32 v57, v51, v51
	v_add_f32_e32 v56, v57, v56
	v_mul_f32_e32 v57, v52, v52
	v_add_f32_e32 v56, v57, v56
	v_mul_f32_e32 v57, v53, v53
	v_add_f32_e32 v56, v57, v56
	v_mul_f32_e32 v57, v54, v54
	v_add_f32_e32 v56, v57, v56
	v_mul_f32_e32 v57, v55, v55
	v_add_f32_e32 v56, v57, v56
	s_nop 1
	v_add_f32_dpp v56, v56, v56 quad_perm:[1,0,3,2] row_mask:0xf bank_mask:0xf
	s_nop 1
	v_add_f32_dpp v56, v56, v56 quad_perm:[2,3,0,1] row_mask:0xf bank_mask:0xf
	s_nop 1
	v_add_f32_dpp v56, v56, v56 row_half_mirror row_mask:0xf bank_mask:0xf
	s_nop 1
	v_add_f32_dpp v56, v56, v56 row_mirror row_mask:0xf bank_mask:0xf
	v_fmamk_f32 v56, v56, 0x3c000000, v206
	v_mul_f32_e32 v57, 0x4b800000, v56
	v_cmp_gt_f32_e32 vcc, s51, v56
	s_nop 1
	v_cndmask_b32_e32 v56, v56, v57, vcc
	v_rsq_f32_e32 v56, v56
	s_nop 0
	v_mul_f32_e32 v57, 0x45800000, v56
	v_cndmask_b32_e32 v56, v56, v57, vcc
	v_lshlrev_b32_e32 v58, 16, v36
	v_and_b32_e32 v59, 0xffff0000, v36
	v_lshlrev_b32_e32 v60, 16, v37
	v_and_b32_e32 v61, 0xffff0000, v37
	v_lshlrev_b32_e32 v62, 16, v38
	v_and_b32_e32 v63, 0xffff0000, v38
	v_lshlrev_b32_e32 v64, 16, v39
	v_and_b32_e32 v65, 0xffff0000, v39
	v_mul_f32_e32 v66, 0xbfb8aa3b, v58
	v_mul_f32_e32 v67, 0xbfb8aa3b, v59
	v_mul_f32_e32 v68, 0xbfb8aa3b, v60
	v_mul_f32_e32 v69, 0xbfb8aa3b, v61
	v_mul_f32_e32 v70, 0xbfb8aa3b, v62
	v_mul_f32_e32 v71, 0xbfb8aa3b, v63
	v_mul_f32_e32 v72, 0xbfb8aa3b, v64
	v_mul_f32_e32 v73, 0xbfb8aa3b, v65
	v_exp_f32_e32 v66, v66
	v_exp_f32_e32 v67, v67
	v_exp_f32_e32 v68, v68
	v_exp_f32_e32 v69, v69
	v_exp_f32_e32 v70, v70
	v_exp_f32_e32 v71, v71
	v_exp_f32_e32 v72, v72
	v_exp_f32_e32 v73, v73
	v_add_f32_e32 v66, 1.0, v66
	v_add_f32_e32 v67, 1.0, v67
	v_add_f32_e32 v68, 1.0, v68
	v_add_f32_e32 v69, 1.0, v69
	v_add_f32_e32 v70, 1.0, v70
	v_add_f32_e32 v71, 1.0, v71
	v_add_f32_e32 v72, 1.0, v72
	v_add_f32_e32 v73, 1.0, v73
	v_rcp_f32_e32 v66, v66
	v_rcp_f32_e32 v67, v67
	v_rcp_f32_e32 v68, v68
	v_rcp_f32_e32 v69, v69
	v_rcp_f32_e32 v70, v70
	v_rcp_f32_e32 v71, v71
	v_rcp_f32_e32 v72, v72
	v_rcp_f32_e32 v73, v73
	v_mul_f32_e32 v66, v66, v58
	v_mul_f32_e32 v67, v67, v59
	v_mul_f32_e32 v68, v68, v60
	v_mul_f32_e32 v69, v69, v61
	v_mul_f32_e32 v70, v70, v62
	v_mul_f32_e32 v71, v71, v63
	v_mul_f32_e32 v72, v72, v64
	v_mul_f32_e32 v73, v73, v65
	v_mul_f32_e32 v48, v56, v48
	v_mul_f32_e32 v49, v56, v49
	v_mul_f32_e32 v50, v56, v50
	v_mul_f32_e32 v51, v56, v51
	v_mul_f32_e32 v52, v56, v52
	v_mul_f32_e32 v53, v56, v53
	v_mul_f32_e32 v54, v56, v54
	v_mul_f32_e32 v55, v56, v55
	v_mul_f32_e32 v48, v2, v48
	v_mul_f32_e32 v49, v3, v49
	v_mul_f32_e32 v50, v4, v50
	v_mul_f32_e32 v51, v5, v51
	v_mul_f32_e32 v52, v6, v52
	v_mul_f32_e32 v53, v7, v53
	v_mul_f32_e32 v54, v8, v54
	v_mul_f32_e32 v55, v9, v55
	v_mul_f32_e32 v48, v66, v48
	v_mul_f32_e32 v49, v67, v49
	v_mul_f32_e32 v50, v68, v50
	v_mul_f32_e32 v51, v69, v51
	v_mul_f32_e32 v52, v70, v52
	v_mul_f32_e32 v53, v71, v53
	v_mul_f32_e32 v54, v72, v54
	v_mul_f32_e32 v55, v73, v55
	v_cvt_pk_bf16_f32 v20, v48, v49
	v_cvt_pk_bf16_f32 v21, v50, v51
	v_cvt_pk_bf16_f32 v22, v52, v53
	v_cvt_pk_bf16_f32 v23, v54, v55
	s_add_u32 s12, s12, 0x8000
	s_addc_u32 s13, s13, 0
	global_store_dwordx4 v13, v[20:23], s[12:13]
	s_waitcnt vmcnt(4)
	v_lshlrev_b32_e32 v48, 16, v24
	v_and_b32_e32 v49, 0xffff0000, v24
	v_lshlrev_b32_e32 v50, 16, v25
	v_and_b32_e32 v51, 0xffff0000, v25
	v_lshlrev_b32_e32 v52, 16, v26
	v_and_b32_e32 v53, 0xffff0000, v26
	v_lshlrev_b32_e32 v54, 16, v27
	v_and_b32_e32 v55, 0xffff0000, v27
	v_mul_f32_e32 v56, v48, v48
	v_mul_f32_e32 v57, v49, v49
	v_add_f32_e32 v56, v56, v57
	v_mul_f32_e32 v57, v50, v50
	v_add_f32_e32 v56, v57, v56
	v_mul_f32_e32 v57, v51, v51
	v_add_f32_e32 v56, v57, v56
	v_mul_f32_e32 v57, v52, v52
	v_add_f32_e32 v56, v57, v56
	v_mul_f32_e32 v57, v53, v53
	v_add_f32_e32 v56, v57, v56
	v_mul_f32_e32 v57, v54, v54
	v_add_f32_e32 v56, v57, v56
	v_mul_f32_e32 v57, v55, v55
	v_add_f32_e32 v56, v57, v56
	s_nop 1
	v_add_f32_dpp v56, v56, v56 quad_perm:[1,0,3,2] row_mask:0xf bank_mask:0xf
	s_nop 1
	v_add_f32_dpp v56, v56, v56 quad_perm:[2,3,0,1] row_mask:0xf bank_mask:0xf
	s_nop 1
	v_add_f32_dpp v56, v56, v56 row_half_mirror row_mask:0xf bank_mask:0xf
	s_nop 1
	v_add_f32_dpp v56, v56, v56 row_mirror row_mask:0xf bank_mask:0xf
	v_fmamk_f32 v56, v56, 0x3c000000, v206
	v_mul_f32_e32 v57, 0x4b800000, v56
	v_cmp_gt_f32_e32 vcc, s51, v56
	s_nop 1
	v_cndmask_b32_e32 v56, v56, v57, vcc
	v_rsq_f32_e32 v56, v56
	s_nop 0
	v_mul_f32_e32 v57, 0x45800000, v56
	v_cndmask_b32_e32 v56, v56, v57, vcc
	v_lshlrev_b32_e32 v58, 16, v40
	v_and_b32_e32 v59, 0xffff0000, v40
	v_lshlrev_b32_e32 v60, 16, v41
	v_and_b32_e32 v61, 0xffff0000, v41
	v_lshlrev_b32_e32 v62, 16, v42
	v_and_b32_e32 v63, 0xffff0000, v42
	v_lshlrev_b32_e32 v64, 16, v43
	v_and_b32_e32 v65, 0xffff0000, v43
	v_mul_f32_e32 v66, 0xbfb8aa3b, v58
	v_mul_f32_e32 v67, 0xbfb8aa3b, v59
	v_mul_f32_e32 v68, 0xbfb8aa3b, v60
	v_mul_f32_e32 v69, 0xbfb8aa3b, v61
	v_mul_f32_e32 v70, 0xbfb8aa3b, v62
	v_mul_f32_e32 v71, 0xbfb8aa3b, v63
	v_mul_f32_e32 v72, 0xbfb8aa3b, v64
	v_mul_f32_e32 v73, 0xbfb8aa3b, v65
	v_exp_f32_e32 v66, v66
; DI float shx(float v, int m) { return __int_as_float(__builtin_amdgcn_ds_bpermute((lane_now() ^ m) << 2, __float_as_int(v))); }
; DI int shx(int v, int m) { return __builtin_amdgcn_ds_bpermute((lane_now() ^ m) << 2, v); }
; DI u16 f2bf(float x) { return (u16)(pk2bf(x, 0.f) & 0xffffu); }
; DI float bfs(short v) { return __uint_as_float(((unsigned)(u16)v) << 16); }
; DI void phase_outnorm_c(int wv_, int vb_, int nvb_, char* ws_, const Ctx& p) {
;     ...
;     for (int q = 0; q < 4; ++q) {
;       float f[8]; float ss = 0.f;
; #pragma unroll
;       for (int j = 0; j < 8; ++j) { f[j] = bfs(ov[q][j]); ss += f[j] * f[j]; }
;       ss += shx(ss, 1); ss += shx(ss, 2); ss += shx(ss, 4); ss += shx(ss, 8);
;       const float rn = rsqrtf(ss * (1.0f / 128.0f) + 1e-6f);
;       bf16x8 o;
; #pragma unroll
;       for (int j = 0; j < 8; ++j) { float gt = bfs(gv[q][j]); float sl = gt * __builtin_amdgcn_rcpf(1.0f + __expf(-gt)); o[j] = (short)f2bf(f[j] * rn * og[j] * sl); }
;       if (ok[q]) *(bf16x8*)(O + ((idx0 + q * stride) >> 4) * 128 + e * 8) = o;
;     }
	v_exp_f32_e32 v67, v67
	v_exp_f32_e32 v68, v68
	v_exp_f32_e32 v69, v69
	v_exp_f32_e32 v70, v70
	v_exp_f32_e32 v71, v71
	v_exp_f32_e32 v72, v72
	v_exp_f32_e32 v73, v73
	v_add_f32_e32 v66, 1.0, v66
	v_add_f32_e32 v67, 1.0, v67
	v_add_f32_e32 v68, 1.0, v68
	v_add_f32_e32 v69, 1.0, v69
	v_add_f32_e32 v70, 1.0, v70
	v_add_f32_e32 v71, 1.0, v71
	v_add_f32_e32 v72, 1.0, v72
	v_add_f32_e32 v73, 1.0, v73
	v_rcp_f32_e32 v66, v66
	v_rcp_f32_e32 v67, v67
	v_rcp_f32_e32 v68, v68
	v_rcp_f32_e32 v69, v69
	v_rcp_f32_e32 v70, v70
	v_rcp_f32_e32 v71, v71
	v_rcp_f32_e32 v72, v72
	v_rcp_f32_e32 v73, v73
	v_mul_f32_e32 v66, v66, v58
	v_mul_f32_e32 v67, v67, v59
	v_mul_f32_e32 v68, v68, v60
	v_mul_f32_e32 v69, v69, v61
	v_mul_f32_e32 v70, v70, v62
	v_mul_f32_e32 v71, v71, v63
	v_mul_f32_e32 v72, v72, v64
	v_mul_f32_e32 v73, v73, v65
	v_mul_f32_e32 v48, v56, v48
	v_mul_f32_e32 v49, v56, v49
	v_mul_f32_e32 v50, v56, v50
	v_mul_f32_e32 v51, v56, v51
	v_mul_f32_e32 v52, v56, v52
	v_mul_f32_e32 v53, v56, v53
	v_mul_f32_e32 v54, v56, v54
	v_mul_f32_e32 v55, v56, v55
	v_mul_f32_e32 v48, v2, v48
	v_mul_f32_e32 v49, v3, v49
	v_mul_f32_e32 v50, v4, v50
	v_mul_f32_e32 v51, v5, v51
	v_mul_f32_e32 v52, v6, v52
	v_mul_f32_e32 v53, v7, v53
	v_mul_f32_e32 v54, v8, v54
	v_mul_f32_e32 v55, v9, v55
	v_mul_f32_e32 v48, v66, v48
	v_mul_f32_e32 v49, v67, v49
	v_mul_f32_e32 v50, v68, v50
	v_mul_f32_e32 v51, v69, v51
	v_mul_f32_e32 v52, v70, v52
	v_mul_f32_e32 v53, v71, v53
	v_mul_f32_e32 v54, v72, v54
	v_mul_f32_e32 v55, v73, v55
	v_cvt_pk_bf16_f32 v24, v48, v49
	v_cvt_pk_bf16_f32 v25, v50, v51
	v_cvt_pk_bf16_f32 v26, v52, v53
	v_cvt_pk_bf16_f32 v27, v54, v55
	s_add_u32 s12, s12, 0x8000
	s_addc_u32 s13, s13, 0
	global_store_dwordx4 v13, v[24:27], s[12:13]
	s_waitcnt vmcnt(3)
	v_lshlrev_b32_e32 v48, 16, v28
	v_and_b32_e32 v49, 0xffff0000, v28
	v_lshlrev_b32_e32 v50, 16, v29
	v_and_b32_e32 v51, 0xffff0000, v29
	v_lshlrev_b32_e32 v52, 16, v30
	v_and_b32_e32 v53, 0xffff0000, v30
	v_lshlrev_b32_e32 v54, 16, v31
	v_and_b32_e32 v55, 0xffff0000, v31
	v_mul_f32_e32 v56, v48, v48
	v_mul_f32_e32 v57, v49, v49
	v_add_f32_e32 v56, v56, v57
	v_mul_f32_e32 v57, v50, v50
	v_add_f32_e32 v56, v57, v56
	v_mul_f32_e32 v57, v51, v51
	v_add_f32_e32 v56, v57, v56
	v_mul_f32_e32 v57, v52, v52
	v_add_f32_e32 v56, v57, v56
	v_mul_f32_e32 v57, v53, v53
	v_add_f32_e32 v56, v57, v56
	v_mul_f32_e32 v57, v54, v54
	v_add_f32_e32 v56, v57, v56
	v_mul_f32_e32 v57, v55, v55
	v_add_f32_e32 v56, v57, v56
	s_nop 1
	v_add_f32_dpp v56, v56, v56 quad_perm:[1,0,3,2] row_mask:0xf bank_mask:0xf
	s_nop 1
	v_add_f32_dpp v56, v56, v56 quad_perm:[2,3,0,1] row_mask:0xf bank_mask:0xf
	s_nop 1
	v_add_f32_dpp v56, v56, v56 row_half_mirror row_mask:0xf bank_mask:0xf
	s_nop 1
	v_add_f32_dpp v56, v56, v56 row_mirror row_mask:0xf bank_mask:0xf
	v_fmamk_f32 v56, v56, 0x3c000000, v206
	v_mul_f32_e32 v57, 0x4b800000, v56
	v_cmp_gt_f32_e32 vcc, s51, v56
	s_nop 1
	v_cndmask_b32_e32 v56, v56, v57, vcc
	v_rsq_f32_e32 v56, v56
	s_nop 0
	v_mul_f32_e32 v57, 0x45800000, v56
	v_cndmask_b32_e32 v56, v56, v57, vcc
	v_lshlrev_b32_e32 v58, 16, v44
	v_and_b32_e32 v59, 0xffff0000, v44
	v_lshlrev_b32_e32 v60, 16, v45
	v_and_b32_e32 v61, 0xffff0000, v45
	v_lshlrev_b32_e32 v62, 16, v46
	v_and_b32_e32 v63, 0xffff0000, v46
	v_lshlrev_b32_e32 v64, 16, v47
	v_and_b32_e32 v65, 0xffff0000, v47
	v_mul_f32_e32 v66, 0xbfb8aa3b, v58
	v_mul_f32_e32 v67, 0xbfb8aa3b, v59
	v_mul_f32_e32 v68, 0xbfb8aa3b, v60
	v_mul_f32_e32 v69, 0xbfb8aa3b, v61
	v_mul_f32_e32 v70, 0xbfb8aa3b, v62
	v_mul_f32_e32 v71, 0xbfb8aa3b, v63
	v_mul_f32_e32 v72, 0xbfb8aa3b, v64
	v_mul_f32_e32 v73, 0xbfb8aa3b, v65
	v_exp_f32_e32 v66, v66
	v_exp_f32_e32 v67, v67
	v_exp_f32_e32 v68, v68
	v_exp_f32_e32 v69, v69
	v_exp_f32_e32 v70, v70
	v_exp_f32_e32 v71, v71
	v_exp_f32_e32 v72, v72
	v_exp_f32_e32 v73, v73
	v_add_f32_e32 v66, 1.0, v66
	v_add_f32_e32 v67, 1.0, v67
	v_add_f32_e32 v68, 1.0, v68
	v_add_f32_e32 v69, 1.0, v69
	v_add_f32_e32 v70, 1.0, v70
	v_add_f32_e32 v71, 1.0, v71
	v_add_f32_e32 v72, 1.0, v72
	v_add_f32_e32 v73, 1.0, v73
	v_rcp_f32_e32 v66, v66
	v_rcp_f32_e32 v67, v67
	v_rcp_f32_e32 v68, v68
	v_rcp_f32_e32 v69, v69
	v_rcp_f32_e32 v70, v70
	v_rcp_f32_e32 v71, v71
	v_rcp_f32_e32 v72, v72
	v_rcp_f32_e32 v73, v73
	v_mul_f32_e32 v66, v66, v58
	v_mul_f32_e32 v67, v67, v59
	v_mul_f32_e32 v68, v68, v60
	v_mul_f32_e32 v69, v69, v61
	v_mul_f32_e32 v70, v70, v62
	v_mul_f32_e32 v71, v71, v63
	v_mul_f32_e32 v72, v72, v64
	v_mul_f32_e32 v73, v73, v65
	v_mul_f32_e32 v48, v56, v48
	v_mul_f32_e32 v49, v56, v49
	v_mul_f32_e32 v50, v56, v50
	v_mul_f32_e32 v51, v56, v51
	v_mul_f32_e32 v52, v56, v52
	v_mul_f32_e32 v53, v56, v53
	v_mul_f32_e32 v54, v56, v54
	v_mul_f32_e32 v55, v56, v55
	v_mul_f32_e32 v48, v2, v48
	v_mul_f32_e32 v49, v3, v49
	v_mul_f32_e32 v50, v4, v50
	v_mul_f32_e32 v51, v5, v51
	v_mul_f32_e32 v52, v6, v52
	v_mul_f32_e32 v53, v7, v53
	v_mul_f32_e32 v54, v8, v54
	v_mul_f32_e32 v55, v9, v55
	v_mul_f32_e32 v48, v66, v48
	v_mul_f32_e32 v49, v67, v49
	v_mul_f32_e32 v50, v68, v50
	v_mul_f32_e32 v51, v69, v51
	v_mul_f32_e32 v52, v70, v52
	v_mul_f32_e32 v53, v71, v53
	v_mul_f32_e32 v54, v72, v54
	v_mul_f32_e32 v55, v73, v55
	v_cvt_pk_bf16_f32 v28, v48, v49
	v_cvt_pk_bf16_f32 v29, v50, v51
	v_cvt_pk_bf16_f32 v30, v52, v53
	v_cvt_pk_bf16_f32 v31, v54, v55
	s_add_u32 s12, s12, 0x8000
	s_addc_u32 s13, s13, 0
	global_store_dwordx4 v13, v[28:31], s[12:13]
	s_add_i32 s10, s10, 384
	s_cmp_lt_u32 s10, 0x800
	s_cbranch_scc1 .Loni_loop
	s_waitcnt vmcnt(0)
	s_mov_b32 s52, 0x6600000
